# v52 + cache policy sc1 (write-through, line dropped from the XCD L2) instead of nt on the P3 XB stores and the P4 SwiGLU activation stores
# speedup vs baseline: 1.0135x; 1.0135x over previous
;     __device__ __forceinline__ void operator()(const f32x4 (&acc)[2][2][4][2], const Unit& u, int wr, int wc, int fr, int fq) const {
;         const int row0 = u.pm * BM + wr * 64 + fr, col0 = u.pn * BM + wc * 32 + 8 * fq;
;         const size_t off0 = (size_t)row0 * D + col0;
;         const bf16_t* __restrict__ xp = XN + tl_off(row0, col0, D); bf16_t* __restrict__ bp = XB + tl_off(row0, col0, D);
;         f32x4 gi[2][2];
; #pragma unroll
;         for (int bj = 0; bj < 2; ++bj)
; #pragma unroll
;             for (int n = 0; n < 2; ++n) { const f32x4 gv = *(const f32x4*)(g1 + col0 + bj * HALF + 4 * n);
;                 gi[bj][n] = (f32x4){__builtin_amdgcn_rcpf(gv[0]), __builtin_amdgcn_rcpf(gv[1]), __builtin_amdgcn_rcpf(gv[2]), __builtin_amdgcn_rcpf(gv[3])}; }
;         u32x4 xa[8][2]; float rr[8], part[8];
; #pragma unroll
;         for (int i = 0; i < 8; ++i) rr[i] = rrow[row0 + (i >> 2) * HALF + (i & 3) * 16];
;     ...
;         EO_LOAD(0); EO_LOAD(1); EO_LOAD(2); EO_LOAD(3);
;         asm volatile("" ::: "memory");
; #pragma unroll
;         for (int i = 0; i < 8; ++i) { const int ai = i >> 2, m = i & 3; const size_t o_ = (size_t)(ai * HALF + m * 16) * D; float p = 0.f;
; #pragma unroll
;             for (int bj = 0; bj < 2; ++bj) { const u32x4 w_ = xa[i][bj];
;                 const f32x4 x0 = {__builtin_bit_cast(float, w_.x << 16), __builtin_bit_cast(float, w_.x & 0xffff0000u), __builtin_bit_cast(float, w_.y << 16), __builtin_bit_cast(float, w_.y & 0xffff0000u)};
;                 const f32x4 x1 = {__builtin_bit_cast(float, w_.z << 16), __builtin_bit_cast(float, w_.z & 0xffff0000u), __builtin_bit_cast(float, w_.w << 16), __builtin_bit_cast(float, w_.w & 0xffff0000u)};
;                 const f32x4 v0 = acc[ai][bj][m][0] + x0 * (gi[bj][0] * rr[i]), v1 = acc[ai][bj][m][1] + x1 * (gi[bj][1] * rr[i]);
;                 u32x4 w; w.x = cvt_pk_bf16(v0[0], v0[1]); w.y = cvt_pk_bf16(v0[2], v0[3]); w.z = cvt_pk_bf16(v1[0], v1[1]); w.w = cvt_pk_bf16(v1[2], v1[3]);
;                 __builtin_nontemporal_store(w, (u32x4*)(bp + (size_t)((ai * 8 + m) * (D / 32) + 4 * bj) * 512));
;                 p += (v0[0] * v0[0] + v0[1] * v0[1]) + (v0[2] * v0[2] + v0[3] * v0[3]) + (v1[0] * v1[0] + v1[1] * v1[1]) + (v1[2] * v1[2] + v1[3] * v1[3]); }
.LBB0_415:
	s_lshl_b32 s0, s83, 8
	v_mov_b32_e32 v208, v198
	v_mov_b32_e32 v10, v197
	s_add_i32 s0, s0, s54
	s_nop 0
	v_add_u32_e32 v164, s0, v10
	s_lshl_b32 s0, s85, 8
	s_or_b32 s0, s0, s55
	v_lshlrev_b32_e32 v11, 3, v208
	v_add_u32_e32 v0, s0, v11
	v_ashrrev_i32_e32 v2, 4, v164
	v_ashrrev_i32_e32 v8, 5, v0
	v_ashrrev_i32_e32 v1, 31, v0
	v_ashrrev_i32_e32 v3, 31, v2
	v_ashrrev_i32_e32 v9, 31, v8
	v_lshl_add_u64 v[0:1], v[0:1], 2, s[38:39]
	v_lshlrev_b64 v[2:3], 14, v[2:3]
	v_lshlrev_b64 v[8:9], 9, v[8:9]
	global_load_dwordx4 v[4:7], v[0:1], off offset:16
	global_load_dwordx4 v[20:23], v[0:1], off
	v_lshl_add_u64 v[2:3], v[8:9], 0, v[2:3]
	v_lshlrev_b32_e32 v8, 5, v10
	v_and_b32_e32 v8, 0x1e0, v8
	global_load_dwordx4 v[170:173], v[0:1], off offset:528
	global_load_dwordx4 v[174:177], v[0:1], off offset:512
	v_and_b32_e32 v0, 24, v11
	v_or3_b32 v2, v0, v8, v2
	v_ashrrev_i32_e32 v165, 31, v164
	v_lshlrev_b64 v[0:1], 1, v[2:3]
	v_lshl_add_u64 v[2:3], v[164:165], 2, s[60:61]
	v_lshl_add_u64 v[192:193], s[62:63], 0, v[0:1]
	global_load_dword v26, v[2:3], off
	global_load_dword v24, v[2:3], off offset:64
	global_load_dword v196, v[2:3], off offset:128
	global_load_dwordx4 v[210:213], v[192:193], off nt
	v_add_co_u32_e32 v8, vcc, s73, v192
	v_lshl_add_u64 v[168:169], s[8:9], 0, v[0:1]
	s_nop 0
	v_addc_co_u32_e32 v9, vcc, 0, v193, vcc
	global_load_dwordx4 v[214:217], v[8:9], off nt
	global_load_dword v194, v[2:3], off offset:192
	global_load_dword v190, v[2:3], off offset:512
	global_load_dword v188, v[2:3], off offset:576
	global_load_dword v186, v[2:3], off offset:640
	global_load_dword v166, v[2:3], off offset:704
	v_add_co_u32_e32 v0, vcc, s74, v192
	s_waitcnt vmcnt(13)
	v_rcp_f32_e32 v180, v6
	v_addc_co_u32_e32 v1, vcc, 0, v193, vcc
	v_add_co_u32_e32 v2, vcc, s75, v192
	s_waitcnt vmcnt(12)
	v_rcp_f32_e32 v182, v20
	v_addc_co_u32_e32 v3, vcc, 0, v193, vcc
	v_add_co_u32_e32 v178, vcc, s76, v192
	v_rcp_f32_e32 v183, v21
	s_nop 0
	v_addc_co_u32_e32 v179, vcc, 0, v193, vcc
	global_load_dwordx4 v[218:221], v[0:1], off offset:-4096 nt
	global_load_dwordx4 v[8:11], v[0:1], off nt
	global_load_dwordx4 v[28:31], v[2:3], off offset:-4096 nt
	global_load_dwordx4 v[12:15], v[2:3], off nt
	global_load_dwordx4 v[16:19], v[178:179], off offset:-4096 nt
	s_nop 0
	global_load_dwordx4 v[0:3], v[178:179], off nt
	v_rcp_f32_e32 v184, v22
	v_rcp_f32_e32 v185, v23
	v_rcp_f32_e32 v178, v4
	v_rcp_f32_e32 v179, v5
	v_rcp_f32_e32 v181, v7
	s_waitcnt vmcnt(15)
	v_pk_mul_f32 v[4:5], v[182:183], v[26:27] op_sel_hi:[1,0]
	s_waitcnt vmcnt(12)
	v_lshlrev_b32_e32 v20, 16, v210
	v_and_b32_e32 v21, 0xffff0000, v210
	v_pk_mul_f32 v[6:7], v[184:185], v[26:27] op_sel_hi:[1,0]
	v_lshlrev_b32_e32 v22, 16, v211
	v_and_b32_e32 v23, 0xffff0000, v211
	v_lshlrev_b32_e32 v210, 16, v212
	v_and_b32_e32 v211, 0xffff0000, v212
	v_pk_fma_f32 v[20:21], v[4:5], v[20:21], v[156:157]
	v_pk_mul_f32 v[4:5], v[26:27], v[178:179] op_sel_hi:[0,1]
	v_lshlrev_b32_e32 v212, 16, v213
	v_and_b32_e32 v213, 0xffff0000, v213
	v_pk_fma_f32 v[22:23], v[6:7], v[22:23], v[158:159]
	v_pk_mul_f32 v[6:7], v[26:27], v[180:181] op_sel_hi:[0,1]
	v_pk_fma_f32 v[152:153], v[4:5], v[210:211], v[152:153]
	v_cvt_pk_bf16_f32 v4, v20, v21
	v_cvt_pk_bf16_f32 v5, v22, v23
	v_pk_fma_f32 v[154:155], v[6:7], v[212:213], v[154:155]
	v_cvt_pk_bf16_f32 v6, v152, v153
	v_rcp_f32_e32 v174, v174
	v_cvt_pk_bf16_f32 v7, v154, v155
	global_store_dwordx4 v[168:169], v[4:7], off sc1
	v_rcp_f32_e32 v175, v175
	v_rcp_f32_e32 v176, v176
	v_mul_f32_e32 v4, v21, v21
	v_mul_f32_e32 v5, v23, v23
	v_fmac_f32_e32 v4, v20, v20
	v_fmac_f32_e32 v5, v22, v22
	v_rcp_f32_e32 v177, v177
	v_add_f32_e32 v4, v4, v5
	v_mul_f32_e32 v5, v153, v153
	v_rcp_f32_e32 v170, v170
	v_rcp_f32_e32 v171, v171
	v_rcp_f32_e32 v172, v172
	v_rcp_f32_e32 v173, v173
	v_fmac_f32_e32 v5, v152, v152
	v_add_f32_e32 v4, v5, v4
	v_mul_f32_e32 v5, v155, v155
	v_fmac_f32_e32 v5, v154, v154
	v_add_f32_e32 v25, v5, v4
	s_waitcnt vmcnt(12)
	v_lshlrev_b32_e32 v4, 16, v214
	v_and_b32_e32 v5, 0xffff0000, v214
	v_lshlrev_b32_e32 v6, 16, v215
	v_and_b32_e32 v7, 0xffff0000, v215
	v_pk_mul_f32 v[152:153], v[26:27], v[174:175] op_sel_hi:[0,1]
	v_pk_mul_f32 v[154:155], v[26:27], v[176:177] op_sel_hi:[0,1]
	v_lshlrev_b32_e32 v20, 16, v216
	v_and_b32_e32 v21, 0xffff0000, v216
	v_pk_fma_f32 v[150:151], v[154:155], v[6:7], v[150:151]
	v_pk_fma_f32 v[148:149], v[152:153], v[4:5], v[148:149]
	v_pk_mul_f32 v[4:5], v[26:27], v[170:171] op_sel_hi:[0,1]
	v_pk_mul_f32 v[6:7], v[26:27], v[172:173] op_sel_hi:[0,1]
	v_add_co_u32_e32 v26, vcc, s73, v168
	v_lshlrev_b32_e32 v22, 16, v217
	v_and_b32_e32 v23, 0xffff0000, v217
	v_pk_fma_f32 v[20:21], v[4:5], v[20:21], v[144:145]
	v_cvt_pk_bf16_f32 v4, v148, v149
	v_cvt_pk_bf16_f32 v5, v150, v151
	v_addc_co_u32_e32 v27, vcc, 0, v169, vcc
	v_pk_fma_f32 v[22:23], v[6:7], v[22:23], v[146:147]
	v_cvt_pk_bf16_f32 v6, v20, v21
	v_pk_mul_f32 v[152:153], v[182:183], v[24:25] op_sel_hi:[1,0]
	v_cvt_pk_bf16_f32 v7, v22, v23
	global_store_dwordx4 v[26:27], v[4:7], off sc1
	v_pk_mul_f32 v[154:155], v[184:185], v[24:25] op_sel_hi:[1,0]
	s_waitcnt vmcnt(7)
; __device__ __forceinline__ unsigned cvt_pk_bf16(float lo, float hi) { unsigned r; asm volatile("v_cvt_pk_bf16_f32 %0, %1, %2" : "=v"(r) : "v"(lo), "v"(hi)); return r; }
; #define EO_LOAD(i) do { const size_t o_ = (size_t)((((i) >> 2) * 8 + ((i) & 3)) * (D / 32)) * 512; xa[i][0] = __builtin_nontemporal_load((const u32x4*)(xp + o_)); xa[i][1] = __builtin_nontemporal_load((const u32x4*)(xp + o_ + 4 * 512)); } while (0)
;     __device__ __forceinline__ void operator()(const f32x4 (&acc)[2][2][4][2], const Unit& u, int wr, int wc, int fr, int fq) const {
;     ...
;         EO_LOAD(0); EO_LOAD(1); EO_LOAD(2); EO_LOAD(3);
;         asm volatile("" ::: "memory");
; #pragma unroll
;         for (int i = 0; i < 8; ++i) { const int ai = i >> 2, m = i & 3; const size_t o_ = (size_t)(ai * HALF + m * 16) * D; float p = 0.f;
; #pragma unroll
;             for (int bj = 0; bj < 2; ++bj) { const u32x4 w_ = xa[i][bj];
;                 const f32x4 x0 = {__builtin_bit_cast(float, w_.x << 16), __builtin_bit_cast(float, w_.x & 0xffff0000u), __builtin_bit_cast(float, w_.y << 16), __builtin_bit_cast(float, w_.y & 0xffff0000u)};
;                 const f32x4 x1 = {__builtin_bit_cast(float, w_.z << 16), __builtin_bit_cast(float, w_.z & 0xffff0000u), __builtin_bit_cast(float, w_.w << 16), __builtin_bit_cast(float, w_.w & 0xffff0000u)};
;                 const f32x4 v0 = acc[ai][bj][m][0] + x0 * (gi[bj][0] * rr[i]), v1 = acc[ai][bj][m][1] + x1 * (gi[bj][1] * rr[i]);
;                 u32x4 w; w.x = cvt_pk_bf16(v0[0], v0[1]); w.y = cvt_pk_bf16(v0[2], v0[3]); w.z = cvt_pk_bf16(v1[0], v1[1]); w.w = cvt_pk_bf16(v1[2], v1[3]);
;                 __builtin_nontemporal_store(w, (u32x4*)(bp + (size_t)((ai * 8 + m) * (D / 32) + 4 * bj) * 512));
;                 p += (v0[0] * v0[0] + v0[1] * v0[1]) + (v0[2] * v0[2] + v0[3] * v0[3]) + (v1[0] * v1[0] + v1[1] * v1[1]) + (v1[2] * v1[2] + v1[3] * v1[3]); }
;             part[i] = p;
;             if (i + 4 < 8) { EO_LOAD((i + 4) & 7); }
;             asm volatile("" ::: "memory"); }
	v_lshlrev_b32_e32 v26, 16, v218
	v_mul_f32_e32 v4, v149, v149
	v_mul_f32_e32 v5, v151, v151
	v_fmac_f32_e32 v4, v148, v148
	v_fmac_f32_e32 v5, v150, v150
	v_add_f32_e32 v4, v4, v5
	v_mul_f32_e32 v5, v21, v21
	v_fmac_f32_e32 v5, v20, v20
	v_add_f32_e32 v4, v5, v4
	v_mul_f32_e32 v5, v23, v23
	v_fmac_f32_e32 v5, v22, v22
	v_add_f32_e32 v4, v5, v4
	v_add_f32_e32 v144, v25, v4
	v_add_co_u32_e32 v4, vcc, s77, v192
	v_and_b32_e32 v27, 0xffff0000, v218
	s_nop 0
	v_addc_co_u32_e32 v5, vcc, 0, v193, vcc
	v_lshlrev_b32_e32 v146, 16, v219
	v_and_b32_e32 v147, 0xffff0000, v219
	v_pk_fma_f32 v[26:27], v[152:153], v[26:27], v[140:141]
	global_load_dwordx4 v[20:23], v[4:5], off offset:-4096 nt
	s_nop 0
	global_load_dwordx4 v[4:7], v[4:5], off nt
	v_lshlrev_b32_e32 v148, 16, v220
	v_and_b32_e32 v149, 0xffff0000, v220
	v_pk_fma_f32 v[142:143], v[154:155], v[146:147], v[142:143]
	v_pk_mul_f32 v[140:141], v[178:179], v[24:25] op_sel_hi:[1,0]
	v_pk_mul_f32 v[146:147], v[180:181], v[24:25] op_sel_hi:[1,0]
	v_mul_f32_e32 v25, v27, v27
	v_pk_fma_f32 v[140:141], v[140:141], v[148:149], v[136:137]
	v_cvt_pk_bf16_f32 v136, v26, v27
	v_fmac_f32_e32 v25, v26, v26
	v_mul_f32_e32 v26, v143, v143
	v_fmac_f32_e32 v26, v142, v142
	v_lshlrev_b32_e32 v150, 16, v221
	v_and_b32_e32 v151, 0xffff0000, v221
	v_add_f32_e32 v25, v25, v26
	v_mul_f32_e32 v26, v141, v141
	v_pk_fma_f32 v[146:147], v[146:147], v[150:151], v[138:139]
	v_fmac_f32_e32 v26, v140, v140
	v_add_f32_e32 v25, v26, v25
	v_mul_f32_e32 v26, v147, v147
	v_add_co_u32_e32 v148, vcc, s74, v168
	v_fmac_f32_e32 v26, v146, v146
	v_cvt_pk_bf16_f32 v137, v142, v143
	v_cvt_pk_bf16_f32 v138, v140, v141
	v_cvt_pk_bf16_f32 v139, v146, v147
	s_nop 0
	v_addc_co_u32_e32 v149, vcc, 0, v169, vcc
	v_add_f32_e32 v142, v26, v25
	s_waitcnt vmcnt(8)
	v_lshlrev_b32_e32 v26, 16, v8
	v_and_b32_e32 v27, 0xffff0000, v8
	v_lshlrev_b32_e32 v8, 16, v9
	v_and_b32_e32 v9, 0xffff0000, v9
	v_pk_mul_f32 v[140:141], v[24:25], v[176:177] op_sel_hi:[0,1]
	global_store_dwordx4 v[148:149], v[136:139], off offset:-4096 sc1
	v_pk_fma_f32 v[134:135], v[140:141], v[8:9], v[134:135]
	v_pk_mul_f32 v[8:9], v[24:25], v[170:171] op_sel_hi:[0,1]
	v_lshlrev_b32_e32 v136, 16, v10
	v_and_b32_e32 v137, 0xffff0000, v10
	v_pk_mul_f32 v[138:139], v[24:25], v[174:175] op_sel_hi:[0,1]
	v_lshlrev_b32_e32 v10, 16, v11
	v_and_b32_e32 v11, 0xffff0000, v11
	v_pk_fma_f32 v[26:27], v[138:139], v[26:27], v[132:133]
	v_pk_mul_f32 v[24:25], v[24:25], v[172:173] op_sel_hi:[0,1]
	v_pk_fma_f32 v[128:129], v[8:9], v[136:137], v[128:129]
	v_cvt_pk_bf16_f32 v8, v26, v27
	v_cvt_pk_bf16_f32 v9, v134, v135
	v_pk_fma_f32 v[24:25], v[24:25], v[10:11], v[130:131]
	v_cvt_pk_bf16_f32 v10, v128, v129
	s_waitcnt vmcnt(8)
	v_lshlrev_b32_e32 v130, 16, v28
	v_cvt_pk_bf16_f32 v11, v24, v25
	global_store_dwordx4 v[148:149], v[8:11], off sc1
	v_and_b32_e32 v131, 0xffff0000, v28
	v_lshlrev_b32_e32 v28, 16, v29
	v_mul_f32_e32 v8, v27, v27
	v_mul_f32_e32 v9, v135, v135
	v_fmac_f32_e32 v8, v26, v26
	v_fmac_f32_e32 v9, v134, v134
	v_add_f32_e32 v8, v8, v9
	v_mul_f32_e32 v9, v129, v129
	v_fmac_f32_e32 v9, v128, v128
	v_add_f32_e32 v8, v9, v8
	v_mul_f32_e32 v9, v25, v25
	v_fmac_f32_e32 v9, v24, v24
	v_add_f32_e32 v8, v9, v8
	v_add_f32_e32 v128, v142, v8
	v_add_co_u32_e32 v8, vcc, s78, v192
	v_pk_mul_f32 v[134:135], v[182:183], v[196:197] op_sel_hi:[1,0]
	s_nop 0
	v_addc_co_u32_e32 v9, vcc, 0, v193, vcc
	v_and_b32_e32 v29, 0xffff0000, v29
	v_lshlrev_b32_e32 v132, 16, v30
	v_and_b32_e32 v133, 0xffff0000, v30
	v_lshlrev_b32_e32 v30, 16, v31
	v_and_b32_e32 v31, 0xffff0000, v31
	v_pk_mul_f32 v[136:137], v[184:185], v[196:197] op_sel_hi:[1,0]
	v_pk_fma_f32 v[124:125], v[134:135], v[130:131], v[124:125]
	v_pk_mul_f32 v[130:131], v[180:181], v[196:197] op_sel_hi:[1,0]
	v_pk_fma_f32 v[126:127], v[136:137], v[28:29], v[126:127]
	v_pk_mul_f32 v[28:29], v[178:179], v[196:197] op_sel_hi:[1,0]
	v_pk_fma_f32 v[122:123], v[130:131], v[30:31], v[122:123]
	v_add_co_u32_e32 v130, vcc, s75, v168
	global_load_dwordx4 v[24:27], v[8:9], off offset:-4096 nt
	s_nop 0
	global_load_dwordx4 v[8:11], v[8:9], off nt
	v_pk_fma_f32 v[120:121], v[28:29], v[132:133], v[120:121]
	v_cvt_pk_bf16_f32 v28, v124, v125
	v_cvt_pk_bf16_f32 v29, v126, v127
	v_addc_co_u32_e32 v131, vcc, 0, v169, vcc
	v_cvt_pk_bf16_f32 v30, v120, v121
	v_cvt_pk_bf16_f32 v31, v122, v123
	global_store_dwordx4 v[130:131], v[28:31], off offset:-4096 sc1
	s_nop 1
	v_mul_f32_e32 v28, v125, v125
	v_mul_f32_e32 v29, v127, v127
	v_fmac_f32_e32 v28, v124, v124
	v_fmac_f32_e32 v29, v126, v126
	v_add_f32_e32 v28, v28, v29
	v_mul_f32_e32 v29, v121, v121
	v_fmac_f32_e32 v29, v120, v120
	v_add_f32_e32 v28, v29, v28
	v_mul_f32_e32 v29, v123, v123
	v_fmac_f32_e32 v29, v122, v122
	v_add_f32_e32 v124, v29, v28
	s_waitcnt vmcnt(11)
	v_lshlrev_b32_e32 v28, 16, v12
	v_and_b32_e32 v29, 0xffff0000, v12
	v_lshlrev_b32_e32 v12, 16, v13
	v_and_b32_e32 v13, 0xffff0000, v13
	v_pk_mul_f32 v[122:123], v[176:177], v[196:197] op_sel_hi:[1,0]
	v_lshlrev_b32_e32 v30, 16, v14
	v_and_b32_e32 v31, 0xffff0000, v14
	v_pk_mul_f32 v[120:121], v[174:175], v[196:197] op_sel_hi:[1,0]
	v_pk_fma_f32 v[118:119], v[122:123], v[12:13], v[118:119]
	v_pk_mul_f32 v[12:13], v[196:197], v[170:171] op_sel_hi:[0,1]
	v_lshlrev_b32_e32 v14, 16, v15
	v_and_b32_e32 v15, 0xffff0000, v15
	v_pk_fma_f32 v[28:29], v[120:121], v[28:29], v[116:117]
	v_pk_mul_f32 v[116:117], v[196:197], v[172:173] op_sel_hi:[0,1]
	v_pk_fma_f32 v[30:31], v[12:13], v[30:31], v[112:113]
	v_cvt_pk_bf16_f32 v12, v28, v29
	v_cvt_pk_bf16_f32 v13, v118, v119
	v_pk_fma_f32 v[114:115], v[116:117], v[14:15], v[114:115]
	v_cvt_pk_bf16_f32 v14, v30, v31
	s_waitcnt vmcnt(10)
; __device__ __forceinline__ unsigned cvt_pk_bf16(float lo, float hi) { unsigned r; asm volatile("v_cvt_pk_bf16_f32 %0, %1, %2" : "=v"(r) : "v"(lo), "v"(hi)); return r; }
; #define EO_LOAD(i) do { const size_t o_ = (size_t)((((i) >> 2) * 8 + ((i) & 3)) * (D / 32)) * 512; xa[i][0] = __builtin_nontemporal_load((const u32x4*)(xp + o_)); xa[i][1] = __builtin_nontemporal_load((const u32x4*)(xp + o_ + 4 * 512)); } while (0)
;     __device__ __forceinline__ void operator()(const f32x4 (&acc)[2][2][4][2], const Unit& u, int wr, int wc, int fr, int fq) const {
;     ...
;         for (int i = 0; i < 8; ++i) { const int ai = i >> 2, m = i & 3; const size_t o_ = (size_t)(ai * HALF + m * 16) * D; float p = 0.f;
; #pragma unroll
;             for (int bj = 0; bj < 2; ++bj) { const u32x4 w_ = xa[i][bj];
;                 const f32x4 x0 = {__builtin_bit_cast(float, w_.x << 16), __builtin_bit_cast(float, w_.x & 0xffff0000u), __builtin_bit_cast(float, w_.y << 16), __builtin_bit_cast(float, w_.y & 0xffff0000u)};
;                 const f32x4 x1 = {__builtin_bit_cast(float, w_.z << 16), __builtin_bit_cast(float, w_.z & 0xffff0000u), __builtin_bit_cast(float, w_.w << 16), __builtin_bit_cast(float, w_.w & 0xffff0000u)};
;                 const f32x4 v0 = acc[ai][bj][m][0] + x0 * (gi[bj][0] * rr[i]), v1 = acc[ai][bj][m][1] + x1 * (gi[bj][1] * rr[i]);
;                 u32x4 w; w.x = cvt_pk_bf16(v0[0], v0[1]); w.y = cvt_pk_bf16(v0[2], v0[3]); w.z = cvt_pk_bf16(v1[0], v1[1]); w.w = cvt_pk_bf16(v1[2], v1[3]);
;                 __builtin_nontemporal_store(w, (u32x4*)(bp + (size_t)((ai * 8 + m) * (D / 32) + 4 * bj) * 512));
;                 p += (v0[0] * v0[0] + v0[1] * v0[1]) + (v0[2] * v0[2] + v0[3] * v0[3]) + (v1[0] * v1[0] + v1[1] * v1[1]) + (v1[2] * v1[2] + v1[3] * v1[3]); }
;             part[i] = p;
;             if (i + 4 < 8) { EO_LOAD((i + 4) & 7); }
	v_lshlrev_b32_e32 v116, 16, v18
	v_cvt_pk_bf16_f32 v15, v114, v115
	global_store_dwordx4 v[130:131], v[12:15], off sc1
	v_and_b32_e32 v117, 0xffff0000, v18
	v_lshlrev_b32_e32 v18, 16, v19
	v_mul_f32_e32 v12, v29, v29
	v_mul_f32_e32 v13, v119, v119
	v_fmac_f32_e32 v12, v28, v28
	v_fmac_f32_e32 v13, v118, v118
	v_add_f32_e32 v12, v12, v13
	v_mul_f32_e32 v13, v31, v31
	v_fmac_f32_e32 v13, v30, v30
	v_add_f32_e32 v12, v13, v12
	v_mul_f32_e32 v13, v115, v115
	v_fmac_f32_e32 v13, v114, v114
	v_add_f32_e32 v12, v13, v12
	v_add_f32_e32 v112, v124, v12
	v_add_co_u32_e32 v12, vcc, s79, v192
	v_lshlrev_b32_e32 v114, 16, v16
	v_and_b32_e32 v115, 0xffff0000, v16
	v_pk_mul_f32 v[118:119], v[182:183], v[194:195] op_sel_hi:[1,0]
	v_addc_co_u32_e32 v13, vcc, 0, v193, vcc
	v_lshlrev_b32_e32 v16, 16, v17
	v_and_b32_e32 v17, 0xffff0000, v17
	v_and_b32_e32 v19, 0xffff0000, v19
	v_pk_mul_f32 v[120:121], v[184:185], v[194:195] op_sel_hi:[1,0]
	v_pk_fma_f32 v[108:109], v[118:119], v[114:115], v[108:109]
	v_pk_mul_f32 v[114:115], v[180:181], v[194:195] op_sel_hi:[1,0]
	v_pk_fma_f32 v[110:111], v[120:121], v[16:17], v[110:111]
	v_pk_mul_f32 v[16:17], v[178:179], v[194:195] op_sel_hi:[1,0]
	v_pk_fma_f32 v[106:107], v[114:115], v[18:19], v[106:107]
	v_add_co_u32_e32 v114, vcc, s76, v168
	global_load_dwordx4 v[28:31], v[12:13], off offset:-4096 nt
	s_nop 0
	global_load_dwordx4 v[12:15], v[12:13], off nt
	v_pk_fma_f32 v[104:105], v[16:17], v[116:117], v[104:105]
	v_cvt_pk_bf16_f32 v16, v108, v109
	v_cvt_pk_bf16_f32 v17, v110, v111
	v_addc_co_u32_e32 v115, vcc, 0, v169, vcc
	v_cvt_pk_bf16_f32 v18, v104, v105
	v_cvt_pk_bf16_f32 v19, v106, v107
	global_store_dwordx4 v[114:115], v[16:19], off offset:-4096 sc1
	s_nop 1
	v_mul_f32_e32 v16, v109, v109
	v_mul_f32_e32 v17, v111, v111
	v_fmac_f32_e32 v16, v108, v108
	v_fmac_f32_e32 v17, v110, v110
	v_add_f32_e32 v16, v16, v17
	v_mul_f32_e32 v17, v105, v105
	v_fmac_f32_e32 v17, v104, v104
	v_add_f32_e32 v16, v17, v16
	v_mul_f32_e32 v17, v107, v107
	v_fmac_f32_e32 v17, v106, v106
	v_add_f32_e32 v108, v17, v16
	s_waitcnt vmcnt(13)
	v_lshlrev_b32_e32 v16, 16, v0
	v_and_b32_e32 v17, 0xffff0000, v0
	v_lshlrev_b32_e32 v0, 16, v1
	v_and_b32_e32 v1, 0xffff0000, v1
	v_pk_mul_f32 v[106:107], v[176:177], v[194:195] op_sel_hi:[1,0]
	v_lshlrev_b32_e32 v18, 16, v2
	v_and_b32_e32 v19, 0xffff0000, v2
	v_pk_mul_f32 v[104:105], v[174:175], v[194:195] op_sel_hi:[1,0]
	v_pk_fma_f32 v[102:103], v[106:107], v[0:1], v[102:103]
	v_pk_mul_f32 v[0:1], v[170:171], v[194:195] op_sel_hi:[1,0]
	v_lshlrev_b32_e32 v2, 16, v3
	v_and_b32_e32 v3, 0xffff0000, v3
	v_pk_fma_f32 v[16:17], v[104:105], v[16:17], v[100:101]
	v_pk_mul_f32 v[100:101], v[172:173], v[194:195] op_sel_hi:[1,0]
	v_pk_fma_f32 v[18:19], v[0:1], v[18:19], v[96:97]
	v_cvt_pk_bf16_f32 v0, v16, v17
	v_cvt_pk_bf16_f32 v1, v102, v103
	v_pk_fma_f32 v[98:99], v[100:101], v[2:3], v[98:99]
	v_cvt_pk_bf16_f32 v2, v18, v19
	s_waitcnt vmcnt(10)
	v_lshlrev_b32_e32 v100, 16, v22
	v_cvt_pk_bf16_f32 v3, v98, v99
	global_store_dwordx4 v[114:115], v[0:3], off sc1
	v_and_b32_e32 v101, 0xffff0000, v22
	v_lshlrev_b32_e32 v22, 16, v23
	v_mul_f32_e32 v0, v17, v17
	v_mul_f32_e32 v1, v103, v103
	v_fmac_f32_e32 v0, v16, v16
	v_fmac_f32_e32 v1, v102, v102
	v_add_f32_e32 v0, v0, v1
	v_mul_f32_e32 v1, v19, v19
	v_fmac_f32_e32 v1, v18, v18
	v_add_f32_e32 v0, v1, v0
	v_mul_f32_e32 v1, v99, v99
	v_fmac_f32_e32 v1, v98, v98
	v_add_f32_e32 v0, v1, v0
	v_add_f32_e32 v96, v108, v0
	v_add_co_u32_e32 v0, vcc, s80, v192
	v_lshlrev_b32_e32 v98, 16, v20
	s_nop 0
	v_addc_co_u32_e32 v1, vcc, 0, v193, vcc
	global_load_dwordx4 v[16:19], v[0:1], off offset:-4096 nt
	s_nop 0
	global_load_dwordx4 v[0:3], v[0:1], off nt
	v_and_b32_e32 v99, 0xffff0000, v20
	v_pk_mul_f32 v[102:103], v[182:183], v[190:191] op_sel_hi:[1,0]
	v_lshlrev_b32_e32 v20, 16, v21
	v_and_b32_e32 v21, 0xffff0000, v21
	v_and_b32_e32 v23, 0xffff0000, v23
	v_pk_mul_f32 v[104:105], v[184:185], v[190:191] op_sel_hi:[1,0]
	v_pk_fma_f32 v[92:93], v[102:103], v[98:99], v[92:93]
	v_pk_mul_f32 v[98:99], v[180:181], v[190:191] op_sel_hi:[1,0]
	v_pk_fma_f32 v[94:95], v[104:105], v[20:21], v[94:95]
	v_pk_mul_f32 v[20:21], v[178:179], v[190:191] op_sel_hi:[1,0]
	v_pk_fma_f32 v[90:91], v[98:99], v[22:23], v[90:91]
	v_add_co_u32_e32 v98, vcc, s77, v168
	v_pk_fma_f32 v[88:89], v[20:21], v[100:101], v[88:89]
	v_cvt_pk_bf16_f32 v20, v92, v93
	v_cvt_pk_bf16_f32 v21, v94, v95
	s_nop 0
	v_addc_co_u32_e32 v99, vcc, 0, v169, vcc
	v_cvt_pk_bf16_f32 v22, v88, v89
	v_cvt_pk_bf16_f32 v23, v90, v91
	global_store_dwordx4 v[98:99], v[20:23], off offset:-4096 sc1
	s_nop 1
	v_mul_f32_e32 v20, v93, v93
	v_mul_f32_e32 v21, v95, v95
	v_fmac_f32_e32 v20, v92, v92
	v_fmac_f32_e32 v21, v94, v94
	v_add_f32_e32 v20, v20, v21
	v_mul_f32_e32 v21, v89, v89
	v_fmac_f32_e32 v21, v88, v88
	v_add_f32_e32 v20, v21, v20
	v_mul_f32_e32 v21, v91, v91
	v_fmac_f32_e32 v21, v90, v90
	v_add_f32_e32 v92, v21, v20
	s_waitcnt vmcnt(13)
	v_lshlrev_b32_e32 v20, 16, v4
	v_and_b32_e32 v21, 0xffff0000, v4
	v_lshlrev_b32_e32 v4, 16, v5
	v_and_b32_e32 v5, 0xffff0000, v5
	v_pk_mul_f32 v[90:91], v[176:177], v[190:191] op_sel_hi:[1,0]
	v_lshlrev_b32_e32 v22, 16, v6
	v_and_b32_e32 v23, 0xffff0000, v6
	v_pk_mul_f32 v[88:89], v[174:175], v[190:191] op_sel_hi:[1,0]
	v_pk_fma_f32 v[86:87], v[90:91], v[4:5], v[86:87]
	v_pk_mul_f32 v[4:5], v[170:171], v[190:191] op_sel_hi:[1,0]
	v_lshlrev_b32_e32 v6, 16, v7
	v_and_b32_e32 v7, 0xffff0000, v7
	v_pk_fma_f32 v[20:21], v[88:89], v[20:21], v[84:85]
	v_pk_mul_f32 v[84:85], v[172:173], v[190:191] op_sel_hi:[1,0]
	v_pk_fma_f32 v[22:23], v[4:5], v[22:23], v[80:81]
	v_cvt_pk_bf16_f32 v4, v20, v21
	v_cvt_pk_bf16_f32 v5, v86, v87
	v_pk_fma_f32 v[82:83], v[84:85], v[6:7], v[82:83]
	v_cvt_pk_bf16_f32 v6, v22, v23
	s_nop 0
	v_cvt_pk_bf16_f32 v7, v82, v83
	global_store_dwordx4 v[98:99], v[4:7], off sc1
	s_nop 1
	v_mul_f32_e32 v4, v21, v21
	v_mul_f32_e32 v5, v87, v87
	v_fmac_f32_e32 v4, v20, v20
	v_fmac_f32_e32 v5, v86, v86
	v_add_f32_e32 v4, v4, v5
	v_mul_f32_e32 v5, v23, v23
	v_fmac_f32_e32 v5, v22, v22
	v_add_f32_e32 v4, v5, v4
	v_mul_f32_e32 v5, v83, v83
	v_fmac_f32_e32 v5, v82, v82
	v_add_f32_e32 v4, v5, v4
	v_add_f32_e32 v80, v92, v4
	s_waitcnt vmcnt(11)
; __device__ __forceinline__ unsigned cvt_pk_bf16(float lo, float hi) { unsigned r; asm volatile("v_cvt_pk_bf16_f32 %0, %1, %2" : "=v"(r) : "v"(lo), "v"(hi)); return r; }
; #define EO_LOAD(i) do { const size_t o_ = (size_t)((((i) >> 2) * 8 + ((i) & 3)) * (D / 32)) * 512; xa[i][0] = __builtin_nontemporal_load((const u32x4*)(xp + o_)); xa[i][1] = __builtin_nontemporal_load((const u32x4*)(xp + o_ + 4 * 512)); } while (0)
;     __device__ __forceinline__ void operator()(const f32x4 (&acc)[2][2][4][2], const Unit& u, int wr, int wc, int fr, int fq) const {
;     ...
;         for (int i = 0; i < 8; ++i) { const int ai = i >> 2, m = i & 3; const size_t o_ = (size_t)(ai * HALF + m * 16) * D; float p = 0.f;
; #pragma unroll
;             for (int bj = 0; bj < 2; ++bj) { const u32x4 w_ = xa[i][bj];
;                 const f32x4 x0 = {__builtin_bit_cast(float, w_.x << 16), __builtin_bit_cast(float, w_.x & 0xffff0000u), __builtin_bit_cast(float, w_.y << 16), __builtin_bit_cast(float, w_.y & 0xffff0000u)};
;                 const f32x4 x1 = {__builtin_bit_cast(float, w_.z << 16), __builtin_bit_cast(float, w_.z & 0xffff0000u), __builtin_bit_cast(float, w_.w << 16), __builtin_bit_cast(float, w_.w & 0xffff0000u)};
;                 const f32x4 v0 = acc[ai][bj][m][0] + x0 * (gi[bj][0] * rr[i]), v1 = acc[ai][bj][m][1] + x1 * (gi[bj][1] * rr[i]);
;                 u32x4 w; w.x = cvt_pk_bf16(v0[0], v0[1]); w.y = cvt_pk_bf16(v0[2], v0[3]); w.z = cvt_pk_bf16(v1[0], v1[1]); w.w = cvt_pk_bf16(v1[2], v1[3]);
;                 __builtin_nontemporal_store(w, (u32x4*)(bp + (size_t)((ai * 8 + m) * (D / 32) + 4 * bj) * 512));
;                 p += (v0[0] * v0[0] + v0[1] * v0[1]) + (v0[2] * v0[2] + v0[3] * v0[3]) + (v1[0] * v1[0] + v1[1] * v1[1]) + (v1[2] * v1[2] + v1[3] * v1[3]); }
;             part[i] = p;
;             if (i + 4 < 8) { EO_LOAD((i + 4) & 7); }
	v_lshlrev_b32_e32 v4, 16, v24
	v_and_b32_e32 v5, 0xffff0000, v24
	v_lshlrev_b32_e32 v6, 16, v25
	v_and_b32_e32 v7, 0xffff0000, v25
	v_pk_mul_f32 v[24:25], v[182:183], v[188:189] op_sel_hi:[1,0]
	v_lshlrev_b32_e32 v20, 16, v26
	v_and_b32_e32 v21, 0xffff0000, v26
	v_pk_fma_f32 v[24:25], v[24:25], v[4:5], v[76:77]
	v_pk_mul_f32 v[4:5], v[178:179], v[188:189] op_sel_hi:[1,0]
	v_lshlrev_b32_e32 v22, 16, v27
	v_and_b32_e32 v23, 0xffff0000, v27
	v_pk_mul_f32 v[26:27], v[184:185], v[188:189] op_sel_hi:[1,0]
	v_pk_fma_f32 v[20:21], v[4:5], v[20:21], v[72:73]
	v_add_co_u32_e32 v72, vcc, s78, v168
	v_pk_fma_f32 v[26:27], v[26:27], v[6:7], v[78:79]
	v_pk_mul_f32 v[6:7], v[180:181], v[188:189] op_sel_hi:[1,0]
	v_cvt_pk_bf16_f32 v4, v24, v25
	v_cvt_pk_bf16_f32 v5, v26, v27
	v_addc_co_u32_e32 v73, vcc, 0, v169, vcc
	v_pk_fma_f32 v[22:23], v[6:7], v[22:23], v[74:75]
	v_cvt_pk_bf16_f32 v6, v20, v21
	s_nop 0
	v_cvt_pk_bf16_f32 v7, v22, v23
	global_store_dwordx4 v[72:73], v[4:7], off offset:-4096 sc1
	s_nop 1
	v_mul_f32_e32 v4, v25, v25
	v_mul_f32_e32 v5, v27, v27
	v_fmac_f32_e32 v4, v24, v24
	v_fmac_f32_e32 v5, v26, v26
	v_add_f32_e32 v4, v4, v5
	v_mul_f32_e32 v5, v21, v21
	v_fmac_f32_e32 v5, v20, v20
	v_add_f32_e32 v4, v5, v4
	v_mul_f32_e32 v5, v23, v23
	v_fmac_f32_e32 v5, v22, v22
	v_add_f32_e32 v24, v5, v4
	s_waitcnt vmcnt(11)
	v_lshlrev_b32_e32 v4, 16, v8
	v_and_b32_e32 v5, 0xffff0000, v8
	v_pk_mul_f32 v[20:21], v[174:175], v[188:189] op_sel_hi:[1,0]
	v_lshlrev_b32_e32 v6, 16, v9
	v_and_b32_e32 v7, 0xffff0000, v9
	v_lshlrev_b32_e32 v8, 16, v10
	v_and_b32_e32 v9, 0xffff0000, v10
	v_pk_mul_f32 v[22:23], v[176:177], v[188:189] op_sel_hi:[1,0]
	v_pk_fma_f32 v[20:21], v[20:21], v[4:5], v[68:69]
	v_pk_mul_f32 v[4:5], v[170:171], v[188:189] op_sel_hi:[1,0]
	v_lshlrev_b32_e32 v10, 16, v11
	v_and_b32_e32 v11, 0xffff0000, v11
	v_pk_fma_f32 v[22:23], v[22:23], v[6:7], v[70:71]
	v_pk_mul_f32 v[6:7], v[172:173], v[188:189] op_sel_hi:[1,0]
	v_pk_fma_f32 v[8:9], v[4:5], v[8:9], v[64:65]
	v_cvt_pk_bf16_f32 v4, v20, v21
	v_cvt_pk_bf16_f32 v5, v22, v23
	v_pk_fma_f32 v[10:11], v[6:7], v[10:11], v[66:67]
	v_cvt_pk_bf16_f32 v6, v8, v9
	s_nop 0
	v_cvt_pk_bf16_f32 v7, v10, v11
	global_store_dwordx4 v[72:73], v[4:7], off sc1
	s_nop 1
	v_mul_f32_e32 v4, v21, v21
	v_mul_f32_e32 v5, v23, v23
	v_fmac_f32_e32 v4, v20, v20
	v_fmac_f32_e32 v5, v22, v22
	v_add_f32_e32 v4, v4, v5
	v_mul_f32_e32 v5, v9, v9
	v_fmac_f32_e32 v5, v8, v8
	v_add_f32_e32 v4, v5, v4
	v_mul_f32_e32 v5, v11, v11
	v_fmac_f32_e32 v5, v10, v10
	v_add_f32_e32 v4, v5, v4
	v_add_f32_e32 v26, v24, v4
	s_waitcnt vmcnt(9)
	v_lshlrev_b32_e32 v4, 16, v28
	v_and_b32_e32 v5, 0xffff0000, v28
	v_pk_mul_f32 v[20:21], v[182:183], v[186:187] op_sel_hi:[1,0]
	v_lshlrev_b32_e32 v6, 16, v29
	v_and_b32_e32 v7, 0xffff0000, v29
	v_lshlrev_b32_e32 v8, 16, v30
	v_and_b32_e32 v9, 0xffff0000, v30
	v_pk_mul_f32 v[22:23], v[184:185], v[186:187] op_sel_hi:[1,0]
	v_pk_fma_f32 v[20:21], v[20:21], v[4:5], v[60:61]
	v_pk_mul_f32 v[4:5], v[178:179], v[186:187] op_sel_hi:[1,0]
	v_add_co_u32_e32 v24, vcc, s79, v168
	v_lshlrev_b32_e32 v10, 16, v31
	v_and_b32_e32 v11, 0xffff0000, v31
	v_pk_fma_f32 v[22:23], v[22:23], v[6:7], v[62:63]
	v_pk_mul_f32 v[6:7], v[180:181], v[186:187] op_sel_hi:[1,0]
	v_pk_fma_f32 v[8:9], v[4:5], v[8:9], v[56:57]
	v_cvt_pk_bf16_f32 v4, v20, v21
	v_cvt_pk_bf16_f32 v5, v22, v23
	v_addc_co_u32_e32 v25, vcc, 0, v169, vcc
	v_pk_fma_f32 v[10:11], v[6:7], v[10:11], v[58:59]
	v_cvt_pk_bf16_f32 v6, v8, v9
	s_nop 0
	v_cvt_pk_bf16_f32 v7, v10, v11
	global_store_dwordx4 v[24:25], v[4:7], off offset:-4096 sc1
	s_nop 1
	v_mul_f32_e32 v4, v21, v21
	v_mul_f32_e32 v5, v23, v23
	v_fmac_f32_e32 v4, v20, v20
	v_fmac_f32_e32 v5, v22, v22
	v_add_f32_e32 v4, v4, v5
	v_mul_f32_e32 v5, v9, v9
	v_fmac_f32_e32 v5, v8, v8
	v_add_f32_e32 v4, v5, v4
	v_mul_f32_e32 v5, v11, v11
	v_fmac_f32_e32 v5, v10, v10
	v_add_f32_e32 v20, v5, v4
	s_waitcnt vmcnt(9)
	v_lshlrev_b32_e32 v4, 16, v12
	v_and_b32_e32 v5, 0xffff0000, v12
	v_lshlrev_b32_e32 v6, 16, v13
	v_and_b32_e32 v7, 0xffff0000, v13
	v_pk_mul_f32 v[12:13], v[174:175], v[186:187] op_sel_hi:[1,0]
	v_lshlrev_b32_e32 v8, 16, v14
	v_and_b32_e32 v9, 0xffff0000, v14
	v_lshlrev_b32_e32 v10, 16, v15
	v_and_b32_e32 v11, 0xffff0000, v15
	v_pk_mul_f32 v[14:15], v[176:177], v[186:187] op_sel_hi:[1,0]
	v_pk_fma_f32 v[12:13], v[12:13], v[4:5], v[52:53]
	v_pk_mul_f32 v[4:5], v[170:171], v[186:187] op_sel_hi:[1,0]
	v_pk_fma_f32 v[14:15], v[14:15], v[6:7], v[54:55]
	v_pk_mul_f32 v[6:7], v[172:173], v[186:187] op_sel_hi:[1,0]
	v_pk_fma_f32 v[8:9], v[4:5], v[8:9], v[48:49]
	v_cvt_pk_bf16_f32 v4, v12, v13
	v_cvt_pk_bf16_f32 v5, v14, v15
	v_pk_fma_f32 v[10:11], v[6:7], v[10:11], v[50:51]
	v_cvt_pk_bf16_f32 v6, v8, v9
	s_nop 0
	v_cvt_pk_bf16_f32 v7, v10, v11
	global_store_dwordx4 v[24:25], v[4:7], off sc1
	s_nop 1
	v_mul_f32_e32 v4, v13, v13
	v_mul_f32_e32 v5, v15, v15
	v_fmac_f32_e32 v4, v12, v12
	v_fmac_f32_e32 v5, v14, v14
	v_add_f32_e32 v4, v4, v5
	v_mul_f32_e32 v5, v9, v9
	v_fmac_f32_e32 v5, v8, v8
	v_add_f32_e32 v4, v5, v4
	v_mul_f32_e32 v5, v11, v11
	v_fmac_f32_e32 v5, v10, v10
	v_add_f32_e32 v4, v5, v4
	v_add_f32_e32 v22, v20, v4
	s_waitcnt vmcnt(7)
; #define EO_LOAD(i) do { const size_t o_ = (size_t)((((i) >> 2) * 8 + ((i) & 3)) * (D / 32)) * 512; xa[i][0] = __builtin_nontemporal_load((const u32x4*)(xp + o_)); xa[i][1] = __builtin_nontemporal_load((const u32x4*)(xp + o_ + 4 * 512)); } while (0)
;     __device__ __forceinline__ void operator()(const f32x4 (&acc)[2][2][4][2], const Unit& u, int wr, int wc, int fr, int fq) const {
;     ...
;                 __builtin_nontemporal_store(w, (u32x4*)(bp + (size_t)((ai * 8 + m) * (D / 32) + 4 * bj) * 512));
;                 p += (v0[0] * v0[0] + v0[1] * v0[1]) + (v0[2] * v0[2] + v0[3] * v0[3]) + (v1[0] * v1[0] + v1[1] * v1[1]) + (v1[2] * v1[2] + v1[3] * v1[3]); }
;             part[i] = p;
;             if (i + 4 < 8) { EO_LOAD((i + 4) & 7); }
;             asm volatile("" ::: "memory"); }
;     ...
; #pragma unroll
;         for (int i = 0; i < 8; ++i) part[i] += __shfl_xor(part[i], 16);
; #pragma unroll
;         for (int i = 0; i < 8; ++i) part[i] += __shfl_xor(part[i], 32);
;         if (fq == 0) {
; #pragma unroll
;             for (int i = 0; i < 8; ++i) atomicAdd(ss + row0 + (i >> 2) * HALF + (i & 3) * 16, part[i]);
;         }
	v_lshlrev_b32_e32 v4, 16, v16
	v_and_b32_e32 v5, 0xffff0000, v16
	v_pk_mul_f32 v[12:13], v[182:183], v[166:167] op_sel_hi:[1,0]
	v_lshlrev_b32_e32 v6, 16, v17
	v_and_b32_e32 v7, 0xffff0000, v17
	v_lshlrev_b32_e32 v8, 16, v18
	v_and_b32_e32 v9, 0xffff0000, v18
	v_pk_mul_f32 v[14:15], v[184:185], v[166:167] op_sel_hi:[1,0]
	v_pk_fma_f32 v[12:13], v[12:13], v[4:5], v[44:45]
	v_pk_mul_f32 v[4:5], v[178:179], v[166:167] op_sel_hi:[1,0]
	v_add_co_u32_e32 v16, vcc, s80, v168
	v_lshlrev_b32_e32 v10, 16, v19
	v_and_b32_e32 v11, 0xffff0000, v19
	v_pk_fma_f32 v[14:15], v[14:15], v[6:7], v[46:47]
	v_pk_mul_f32 v[6:7], v[180:181], v[166:167] op_sel_hi:[1,0]
	v_pk_fma_f32 v[8:9], v[4:5], v[8:9], v[40:41]
	v_cvt_pk_bf16_f32 v4, v12, v13
	v_cvt_pk_bf16_f32 v5, v14, v15
	v_addc_co_u32_e32 v17, vcc, 0, v169, vcc
	v_pk_fma_f32 v[10:11], v[6:7], v[10:11], v[42:43]
	v_cvt_pk_bf16_f32 v6, v8, v9
	v_pk_mul_f32 v[18:19], v[174:175], v[166:167] op_sel_hi:[1,0]
	v_cvt_pk_bf16_f32 v7, v10, v11
	global_store_dwordx4 v[16:17], v[4:7], off offset:-4096 sc1
	v_pk_mul_f32 v[20:21], v[176:177], v[166:167] op_sel_hi:[1,0]
	v_cmp_eq_u32_e32 vcc, 0, v208
	s_waitcnt vmcnt(7)
	v_lshlrev_b32_e32 v4, 16, v0
	v_and_b32_e32 v5, 0xffff0000, v0
	v_lshlrev_b32_e32 v0, 16, v1
	v_and_b32_e32 v1, 0xffff0000, v1
	v_lshlrev_b32_e32 v6, 16, v2
	v_and_b32_e32 v7, 0xffff0000, v2
	v_lshlrev_b32_e32 v2, 16, v3
	v_and_b32_e32 v3, 0xffff0000, v3
	v_pk_fma_f32 v[20:21], v[20:21], v[0:1], v[38:39]
	v_pk_fma_f32 v[4:5], v[18:19], v[4:5], v[36:37]
	v_pk_mul_f32 v[0:1], v[170:171], v[166:167] op_sel_hi:[1,0]
	v_pk_mul_f32 v[18:19], v[172:173], v[166:167] op_sel_hi:[1,0]
	v_pk_fma_f32 v[6:7], v[0:1], v[6:7], v[32:33]
	v_pk_fma_f32 v[18:19], v[18:19], v[2:3], v[34:35]
	v_cvt_pk_bf16_f32 v0, v4, v5
	v_cvt_pk_bf16_f32 v1, v20, v21
	v_cvt_pk_bf16_f32 v2, v6, v7
	s_nop 0
	v_cvt_pk_bf16_f32 v3, v18, v19
	global_store_dwordx4 v[16:17], v[0:3], off sc1
	s_nop 1
	v_mul_f32_e32 v2, v13, v13
	v_mul_f32_e32 v3, v15, v15
	v_fmac_f32_e32 v2, v12, v12
	v_fmac_f32_e32 v3, v14, v14
	v_mul_f32_e32 v1, v9, v9
	v_add_f32_e32 v2, v2, v3
	v_mul_f32_e32 v3, v5, v5
	v_fmac_f32_e32 v1, v8, v8
	v_fmac_f32_e32 v3, v4, v4
	v_mul_f32_e32 v4, v21, v21
	v_add_f32_e32 v1, v1, v2
	v_mul_f32_e32 v2, v7, v7
	v_fmac_f32_e32 v4, v20, v20
	v_mul_f32_e32 v0, v11, v11
	v_fmac_f32_e32 v2, v6, v6
	v_add_f32_e32 v3, v3, v4
	v_fmac_f32_e32 v0, v10, v10
	v_add_f32_e32 v2, v2, v3
	ds_bpermute_b32 v3, v200, v144
	ds_bpermute_b32 v4, v200, v128
	ds_bpermute_b32 v5, v200, v112
	v_add_f32_e32 v0, v0, v1
	v_mul_f32_e32 v1, v19, v19
	v_fmac_f32_e32 v1, v18, v18
	v_add_f32_e32 v1, v1, v2
	v_add_f32_e32 v7, v0, v1
	s_waitcnt lgkmcnt(2)
	v_add_f32_e32 v0, v144, v3
	s_waitcnt lgkmcnt(1)
	v_add_f32_e32 v1, v128, v4
	s_waitcnt lgkmcnt(0)
	v_add_f32_e32 v2, v112, v5
	ds_bpermute_b32 v3, v200, v96
	ds_bpermute_b32 v4, v200, v80
	ds_bpermute_b32 v5, v200, v26
	ds_bpermute_b32 v8, v200, v22
	ds_bpermute_b32 v9, v200, v7
	s_waitcnt lgkmcnt(4)
	v_add_f32_e32 v3, v96, v3
	s_waitcnt lgkmcnt(3)
	v_add_f32_e32 v4, v80, v4
	s_waitcnt lgkmcnt(2)
	v_add_f32_e32 v6, v26, v5
	s_waitcnt lgkmcnt(1)
	v_add_f32_e32 v8, v22, v8
	s_waitcnt lgkmcnt(0)
	v_add_f32_e32 v10, v7, v9
	ds_bpermute_b32 v5, v201, v0
	ds_bpermute_b32 v7, v201, v1
	ds_bpermute_b32 v9, v201, v2
	ds_bpermute_b32 v11, v201, v3
	ds_bpermute_b32 v12, v201, v4
	ds_bpermute_b32 v13, v201, v6
	ds_bpermute_b32 v14, v201, v8
	ds_bpermute_b32 v15, v201, v10
	s_and_saveexec_b64 s[18:19], vcc
	s_cbranch_execz .LBB0_417
	s_waitcnt lgkmcnt(6)
	v_add_f32_e32 v7, v1, v7
	v_add_f32_e32 v5, v0, v5
	v_lshl_add_u64 v[0:1], v[164:165], 2, s[10:11]
	s_waitcnt lgkmcnt(0)
	v_add_f32_e32 v10, v10, v15
	v_add_f32_e32 v8, v8, v14
	v_add_f32_e32 v6, v6, v13
	v_add_f32_e32 v4, v4, v12
	v_add_f32_e32 v3, v3, v11
	v_add_f32_e32 v2, v2, v9
	global_atomic_add_f32 v[0:1], v5, off
	global_atomic_add_f32 v[0:1], v7, off offset:64
	global_atomic_add_f32 v[0:1], v2, off offset:128
	global_atomic_add_f32 v[0:1], v3, off offset:192
	global_atomic_add_f32 v[0:1], v4, off offset:512
	global_atomic_add_f32 v[0:1], v6, off offset:576
	global_atomic_add_f32 v[0:1], v8, off offset:640
	global_atomic_add_f32 v[0:1], v10, off offset:704

; __host__ __device__ __forceinline__ size_t tl_off(int row, int k, int K) { return ((((size_t)(row >> 4) * (size_t)(K >> 5)) + (size_t)(k >> 5)) << 9) + (size_t)((row & 15) * 32 + (k & 31)); }
; __device__ __forceinline__ unsigned cvt_pk_bf16(float lo, float hi) { unsigned r; asm volatile("v_cvt_pk_bf16_f32 %0, %1, %2" : "=v"(r) : "v"(lo), "v"(hi)); return r; }
;     __device__ __forceinline__ void operator()(const f32x4 (&acc)[2][2][4][2], const Unit& u, int wr, int wc, int fr, int fq) const {
;         const int row0 = u.pm * BM + wr * 64 + fr, col0 = u.pn * HALF + wc * 32 + 8 * fq;
;         float sv[8];
; #pragma unroll
;         for (int i = 0; i < 8; ++i) sv[i] = ssl[wr * 64 + fr + (i >> 2) * HALF + (i & 3) * 16];
;         asm volatile("" ::: "memory");
; #pragma unroll
;         for (int i = 0; i < 8; ++i) { const int ai = i >> 2, m = i & 3;
;             const float rstd = __builtin_amdgcn_rsqf(sv[i] * (1.0f / (float)D) + EPS), ne = -LOG2E * rstd, r2 = rstd * rstd;
;             unsigned w[4];
; #pragma unroll
;             for (int n = 0; n < 2; ++n)
; #pragma unroll
;                 for (int h = 0; h < 2; ++h) {
;                     const f32x2 g = {acc[ai][0][m][n][2 * h], acc[ai][0][m][n][2 * h + 1]}, up = {acc[ai][1][m][n][2 * h], acc[ai][1][m][n][2 * h + 1]};
;                     const f32x2 t = g * ne; f32x2 e; e.x = __builtin_amdgcn_exp2f(t.x); e.y = __builtin_amdgcn_exp2f(t.y);
;                     const f32x2 d = e + 1.0f; f32x2 r; r.x = __builtin_amdgcn_rcpf(d.x); r.y = __builtin_amdgcn_rcpf(d.y);
;                     const f32x2 a = (g * up) * (r * r2);
;                     w[2 * n + h] = cvt_pk_bf16(a.x, a.y); }
;             __builtin_nontemporal_store((u32x4){w[0], w[1], w[2], w[3]}, (u32x4*)(ACT + tl_off(row0 + ai * HALF + m * 16, col0, FF)));
;         }
.LBB0_491:
	v_mov_b32_e32 v128, v148
	v_mov_b32_e32 v136, v149
	s_add_i32 s1, s22, s62
	v_lshlrev_b32_e32 v157, 3, v136
	v_lshl_add_u32 v136, v128, 2, s74
	ds_read2_b32 v[158:159], v136 offset1:16
	ds_read2_b32 v[142:143], v136 offset0:32 offset1:48
	ds_read2_b32 v[140:141], v136 offset0:128 offset1:144
	ds_read2_b32 v[138:139], v136 offset0:160 offset1:176
	v_add_u32_e32 v156, s1, v128
	s_waitcnt lgkmcnt(3)
	v_fmamk_f32 v137, v158, 0x3a800000, v155
	v_rsq_f32_e32 v158, v137
	v_lshlrev_b32_e32 v162, 5, v128
	v_pk_mul_f32 v[126:127], v[122:123], v[126:127]
	v_mul_f32_e32 v128, 0xbfb8aa3b, v158
	v_pk_mul_f32 v[160:161], v[120:121], v[128:129] op_sel_hi:[1,0]
	v_pk_mul_f32 v[122:123], v[122:123], v[128:129] op_sel_hi:[1,0]
	v_exp_f32_e32 v160, v160
	v_exp_f32_e32 v161, v161
	v_exp_f32_e32 v122, v122
	v_exp_f32_e32 v123, v123
	v_mul_f32_e32 v158, v158, v158
	v_pk_add_f32 v[160:161], v[160:161], 1.0 op_sel_hi:[1,0]
	v_pk_mul_f32 v[120:121], v[120:121], v[124:125]
	v_rcp_f32_e32 v160, v160
	v_rcp_f32_e32 v161, v161
	v_pk_add_f32 v[122:123], v[122:123], 1.0 op_sel_hi:[1,0]
	s_lshl_b32 s0, s0, 7
	v_rcp_f32_e32 v122, v122
	v_pk_mul_f32 v[124:125], v[158:159], v[160:161] op_sel_hi:[0,1]
	v_rcp_f32_e32 v123, v123
	v_pk_mul_f32 v[120:121], v[120:121], v[124:125]
	v_pk_mul_f32 v[124:125], v[112:113], v[128:129] op_sel_hi:[1,0]
	v_cvt_pk_bf16_f32 v120, v120, v121
	v_pk_mul_f32 v[122:123], v[158:159], v[122:123] op_sel_hi:[0,1]
	v_exp_f32_e32 v124, v124
	v_exp_f32_e32 v125, v125
	v_pk_mul_f32 v[122:123], v[126:127], v[122:123]
	v_pk_mul_f32 v[112:113], v[112:113], v[116:117]
	v_cvt_pk_bf16_f32 v121, v122, v123
	v_pk_add_f32 v[122:123], v[124:125], 1.0 op_sel_hi:[1,0]
	v_pk_mul_f32 v[124:125], v[114:115], v[128:129] op_sel_hi:[1,0]
	v_rcp_f32_e32 v122, v122
	v_exp_f32_e32 v124, v124
	v_exp_f32_e32 v125, v125
	v_rcp_f32_e32 v123, v123
	v_pk_mul_f32 v[114:115], v[114:115], v[118:119]
	s_or_b32 s0, s0, s63
	v_pk_add_f32 v[116:117], v[124:125], 1.0 op_sel_hi:[1,0]
	v_pk_mul_f32 v[118:119], v[158:159], v[122:123] op_sel_hi:[0,1]
	v_rcp_f32_e32 v116, v116
	v_rcp_f32_e32 v117, v117
	v_pk_mul_f32 v[112:113], v[112:113], v[118:119]
	v_add_u32_e32 v136, s0, v157
	v_cvt_pk_bf16_f32 v122, v112, v113
	v_pk_mul_f32 v[112:113], v[158:159], v[116:117] op_sel_hi:[0,1]
	v_pk_mul_f32 v[112:113], v[114:115], v[112:113]
	v_fmamk_f32 v114, v159, 0x3a800000, v155
	v_rsq_f32_e32 v115, v114
	v_ashrrev_i32_e32 v136, 5, v136
	v_ashrrev_i32_e32 v137, 31, v136
	v_cvt_pk_bf16_f32 v123, v112, v113
	v_mul_f32_e32 v114, 0xbfb8aa3b, v115
	v_pk_mul_f32 v[116:117], v[104:105], v[114:115] op_sel_hi:[1,0]
	v_ashrrev_i32_e32 v112, 4, v156
	v_exp_f32_e32 v116, v116
	v_exp_f32_e32 v117, v117
	v_pk_mul_f32 v[110:111], v[106:107], v[110:111]
	v_pk_mul_f32 v[106:107], v[106:107], v[114:115] op_sel_hi:[1,0]
	v_and_b32_e32 v162, 0x1e0, v162
	v_mad_i64_i32 v[112:113], s[0:1], v112, s75, v[136:137]
	v_pk_add_f32 v[116:117], v[116:117], 1.0 op_sel_hi:[1,0]
	v_exp_f32_e32 v106, v106
	v_exp_f32_e32 v107, v107
	v_and_or_b32 v157, v157, 24, v162
	v_lshlrev_b64 v[112:113], 10, v[112:113]
	v_rcp_f32_e32 v116, v116
	v_rcp_f32_e32 v117, v117
	v_lshl_add_u64 v[112:113], s[24:25], 0, v[112:113]
	v_lshlrev_b32_e32 v128, 1, v157
	v_lshl_add_u64 v[112:113], v[112:113], 0, v[128:129]
	global_store_dwordx4 v[112:113], v[120:123], off sc1
	v_mul_f32_e32 v112, v115, v115
	v_pk_add_f32 v[106:107], v[106:107], 1.0 op_sel_hi:[1,0]
	v_pk_mul_f32 v[104:105], v[104:105], v[108:109]
	v_pk_mul_f32 v[108:109], v[112:113], v[116:117] op_sel_hi:[0,1]
	v_rcp_f32_e32 v106, v106
	v_rcp_f32_e32 v107, v107
	v_pk_mul_f32 v[104:105], v[104:105], v[108:109]
	v_pk_mul_f32 v[108:109], v[96:97], v[114:115] op_sel_hi:[1,0]
	v_cvt_pk_bf16_f32 v104, v104, v105
	v_pk_mul_f32 v[106:107], v[112:113], v[106:107] op_sel_hi:[0,1]
	v_exp_f32_e32 v108, v108
	v_exp_f32_e32 v109, v109
	v_pk_mul_f32 v[106:107], v[110:111], v[106:107]
	v_pk_mul_f32 v[96:97], v[96:97], v[100:101]
	v_cvt_pk_bf16_f32 v105, v106, v107
	v_pk_add_f32 v[106:107], v[108:109], 1.0 op_sel_hi:[1,0]
	v_pk_mul_f32 v[108:109], v[98:99], v[114:115] op_sel_hi:[1,0]
	v_rcp_f32_e32 v106, v106
	v_exp_f32_e32 v108, v108
	v_exp_f32_e32 v109, v109
	v_rcp_f32_e32 v107, v107
	v_pk_mul_f32 v[98:99], v[98:99], v[102:103]
	v_pk_mul_f32 v[94:95], v[90:91], v[94:95]
	v_pk_add_f32 v[100:101], v[108:109], 1.0 op_sel_hi:[1,0]
	v_pk_mul_f32 v[102:103], v[112:113], v[106:107] op_sel_hi:[0,1]
	v_rcp_f32_e32 v100, v100
	v_rcp_f32_e32 v101, v101
	v_pk_mul_f32 v[96:97], v[96:97], v[102:103]
	v_pk_mul_f32 v[78:79], v[74:75], v[78:79]
	v_cvt_pk_bf16_f32 v106, v96, v97
	v_pk_mul_f32 v[96:97], v[112:113], v[100:101] op_sel_hi:[0,1]
	v_pk_mul_f32 v[96:97], v[98:99], v[96:97]
	v_pk_mul_f32 v[46:47], v[42:43], v[46:47]
	v_cvt_pk_bf16_f32 v107, v96, v97
	s_waitcnt lgkmcnt(2)
; __host__ __device__ __forceinline__ size_t tl_off(int row, int k, int K) { return ((((size_t)(row >> 4) * (size_t)(K >> 5)) + (size_t)(k >> 5)) << 9) + (size_t)((row & 15) * 32 + (k & 31)); }
; __device__ __forceinline__ unsigned cvt_pk_bf16(float lo, float hi) { unsigned r; asm volatile("v_cvt_pk_bf16_f32 %0, %1, %2" : "=v"(r) : "v"(lo), "v"(hi)); return r; }
;     __device__ __forceinline__ void operator()(const f32x4 (&acc)[2][2][4][2], const Unit& u, int wr, int wc, int fr, int fq) const {
;     ...
;         for (int i = 0; i < 8; ++i) { const int ai = i >> 2, m = i & 3;
;             const float rstd = __builtin_amdgcn_rsqf(sv[i] * (1.0f / (float)D) + EPS), ne = -LOG2E * rstd, r2 = rstd * rstd;
;             unsigned w[4];
; #pragma unroll
;             for (int n = 0; n < 2; ++n)
; #pragma unroll
;                 for (int h = 0; h < 2; ++h) {
;                     const f32x2 g = {acc[ai][0][m][n][2 * h], acc[ai][0][m][n][2 * h + 1]}, up = {acc[ai][1][m][n][2 * h], acc[ai][1][m][n][2 * h + 1]};
;                     const f32x2 t = g * ne; f32x2 e; e.x = __builtin_amdgcn_exp2f(t.x); e.y = __builtin_amdgcn_exp2f(t.y);
;                     const f32x2 d = e + 1.0f; f32x2 r; r.x = __builtin_amdgcn_rcpf(d.x); r.y = __builtin_amdgcn_rcpf(d.y);
;                     const f32x2 a = (g * up) * (r * r2);
;                     w[2 * n + h] = cvt_pk_bf16(a.x, a.y); }
;             __builtin_nontemporal_store((u32x4){w[0], w[1], w[2], w[3]}, (u32x4*)(ACT + tl_off(row0 + ai * HALF + m * 16, col0, FF)));
	v_fmamk_f32 v97, v142, 0x3a800000, v155
	v_rsq_f32_e32 v99, v97
	v_add_u32_e32 v96, 16, v156
	v_ashrrev_i32_e32 v96, 4, v96
	v_mad_i64_i32 v[96:97], s[0:1], v96, s75, v[136:137]
	v_mul_f32_e32 v98, 0xbfb8aa3b, v99
	v_pk_mul_f32 v[100:101], v[88:89], v[98:99] op_sel_hi:[1,0]
	v_pk_mul_f32 v[90:91], v[90:91], v[98:99] op_sel_hi:[1,0]
	v_exp_f32_e32 v100, v100
	v_exp_f32_e32 v101, v101
	v_exp_f32_e32 v90, v90
	v_exp_f32_e32 v91, v91
	v_lshlrev_b64 v[96:97], 10, v[96:97]
	v_pk_add_f32 v[100:101], v[100:101], 1.0 op_sel_hi:[1,0]
	v_lshl_add_u64 v[96:97], s[24:25], 0, v[96:97]
	v_rcp_f32_e32 v100, v100
	v_rcp_f32_e32 v101, v101
	v_lshl_add_u64 v[96:97], v[96:97], 0, v[128:129]
	global_store_dwordx4 v[96:97], v[104:107], off sc1
	v_mul_f32_e32 v96, v99, v99
	v_pk_add_f32 v[90:91], v[90:91], 1.0 op_sel_hi:[1,0]
	v_pk_mul_f32 v[88:89], v[88:89], v[92:93]
	v_pk_mul_f32 v[92:93], v[96:97], v[100:101] op_sel_hi:[0,1]
	v_rcp_f32_e32 v90, v90
	v_rcp_f32_e32 v91, v91
	v_pk_mul_f32 v[88:89], v[88:89], v[92:93]
	v_pk_mul_f32 v[92:93], v[80:81], v[98:99] op_sel_hi:[1,0]
	v_cvt_pk_bf16_f32 v88, v88, v89
	v_pk_mul_f32 v[90:91], v[96:97], v[90:91] op_sel_hi:[0,1]
	v_exp_f32_e32 v92, v92
	v_exp_f32_e32 v93, v93
	v_pk_mul_f32 v[90:91], v[94:95], v[90:91]
	v_pk_mul_f32 v[80:81], v[80:81], v[84:85]
	v_cvt_pk_bf16_f32 v89, v90, v91
	v_pk_add_f32 v[90:91], v[92:93], 1.0 op_sel_hi:[1,0]
	v_pk_mul_f32 v[92:93], v[82:83], v[98:99] op_sel_hi:[1,0]
	v_rcp_f32_e32 v90, v90
	v_exp_f32_e32 v92, v92
	v_exp_f32_e32 v93, v93
	v_rcp_f32_e32 v91, v91
	v_pk_mul_f32 v[82:83], v[82:83], v[86:87]
	v_pk_mul_f32 v[30:31], v[26:27], v[30:31]
	v_pk_add_f32 v[84:85], v[92:93], 1.0 op_sel_hi:[1,0]
	v_pk_mul_f32 v[86:87], v[96:97], v[90:91] op_sel_hi:[0,1]
	v_rcp_f32_e32 v84, v84
	v_rcp_f32_e32 v85, v85
	v_pk_mul_f32 v[80:81], v[80:81], v[86:87]
	v_pk_mul_f32 v[14:15], v[10:11], v[14:15]
	v_cvt_pk_bf16_f32 v90, v80, v81
	v_pk_mul_f32 v[80:81], v[96:97], v[84:85] op_sel_hi:[0,1]
	v_pk_mul_f32 v[80:81], v[82:83], v[80:81]
	s_andn2_b64 vcc, exec, s[4:5]
	v_cvt_pk_bf16_f32 v91, v80, v81
	v_fmamk_f32 v81, v143, 0x3a800000, v155
	v_rsq_f32_e32 v83, v81
	v_add_u32_e32 v80, 32, v156
	v_ashrrev_i32_e32 v80, 4, v80
	v_mad_i64_i32 v[80:81], s[0:1], v80, s75, v[136:137]
	v_mul_f32_e32 v82, 0xbfb8aa3b, v83
	v_pk_mul_f32 v[84:85], v[72:73], v[82:83] op_sel_hi:[1,0]
	v_pk_mul_f32 v[74:75], v[74:75], v[82:83] op_sel_hi:[1,0]
	v_exp_f32_e32 v84, v84
	v_exp_f32_e32 v85, v85
	v_exp_f32_e32 v74, v74
	v_exp_f32_e32 v75, v75
	v_lshlrev_b64 v[80:81], 10, v[80:81]
	v_pk_add_f32 v[84:85], v[84:85], 1.0 op_sel_hi:[1,0]
	v_lshl_add_u64 v[80:81], s[24:25], 0, v[80:81]
	v_rcp_f32_e32 v84, v84
	v_rcp_f32_e32 v85, v85
	v_lshl_add_u64 v[80:81], v[80:81], 0, v[128:129]
	global_store_dwordx4 v[80:81], v[88:91], off sc1
	v_mul_f32_e32 v80, v83, v83
	v_pk_add_f32 v[74:75], v[74:75], 1.0 op_sel_hi:[1,0]
	v_pk_mul_f32 v[72:73], v[72:73], v[76:77]
	v_pk_mul_f32 v[76:77], v[80:81], v[84:85] op_sel_hi:[0,1]
	v_rcp_f32_e32 v74, v74
	v_rcp_f32_e32 v75, v75
	v_pk_mul_f32 v[72:73], v[72:73], v[76:77]
	v_pk_mul_f32 v[76:77], v[60:61], v[82:83] op_sel_hi:[1,0]
	v_cvt_pk_bf16_f32 v72, v72, v73
	v_pk_mul_f32 v[74:75], v[80:81], v[74:75] op_sel_hi:[0,1]
	v_exp_f32_e32 v76, v76
	v_exp_f32_e32 v77, v77
	v_pk_mul_f32 v[74:75], v[78:79], v[74:75]
	v_pk_mul_f32 v[60:61], v[60:61], v[64:65]
	v_cvt_pk_bf16_f32 v73, v74, v75
	v_pk_add_f32 v[74:75], v[76:77], 1.0 op_sel_hi:[1,0]
	v_pk_mul_f32 v[76:77], v[62:63], v[82:83] op_sel_hi:[1,0]
	v_rcp_f32_e32 v74, v74
	v_exp_f32_e32 v76, v76
	v_exp_f32_e32 v77, v77
	v_rcp_f32_e32 v75, v75
	v_pk_mul_f32 v[62:63], v[62:63], v[66:67]
	s_mov_b64 s[4:5], -1
	v_pk_add_f32 v[64:65], v[76:77], 1.0 op_sel_hi:[1,0]
	v_pk_mul_f32 v[66:67], v[80:81], v[74:75] op_sel_hi:[0,1]
	v_rcp_f32_e32 v64, v64
	v_rcp_f32_e32 v65, v65
	v_pk_mul_f32 v[60:61], v[60:61], v[66:67]
	v_pk_mul_f32 v[66:67], v[58:59], v[70:71]
	v_cvt_pk_bf16_f32 v74, v60, v61
	v_pk_mul_f32 v[60:61], v[80:81], v[64:65] op_sel_hi:[0,1]
	v_pk_mul_f32 v[60:61], v[62:63], v[60:61]
	s_nop 0
	v_cvt_pk_bf16_f32 v75, v60, v61
	s_waitcnt lgkmcnt(1)
	v_fmamk_f32 v61, v140, 0x3a800000, v155
	v_rsq_f32_e32 v63, v61
	v_add_u32_e32 v60, 48, v156
	v_ashrrev_i32_e32 v60, 4, v60
	v_mad_i64_i32 v[60:61], s[0:1], v60, s75, v[136:137]
	v_mul_f32_e32 v62, 0xbfb8aa3b, v63
	v_pk_mul_f32 v[64:65], v[56:57], v[62:63] op_sel_hi:[1,0]
	v_pk_mul_f32 v[58:59], v[58:59], v[62:63] op_sel_hi:[1,0]
	v_exp_f32_e32 v64, v64
	v_exp_f32_e32 v65, v65
	v_exp_f32_e32 v58, v58
	v_exp_f32_e32 v59, v59
	v_lshlrev_b64 v[60:61], 10, v[60:61]
	v_pk_add_f32 v[64:65], v[64:65], 1.0 op_sel_hi:[1,0]
	v_lshl_add_u64 v[60:61], s[24:25], 0, v[60:61]
	v_rcp_f32_e32 v64, v64
	v_rcp_f32_e32 v65, v65
	v_lshl_add_u64 v[60:61], v[60:61], 0, v[128:129]
	global_store_dwordx4 v[60:61], v[72:75], off sc1
	v_mul_f32_e32 v60, v63, v63
	v_pk_add_f32 v[58:59], v[58:59], 1.0 op_sel_hi:[1,0]
	v_pk_mul_f32 v[56:57], v[56:57], v[68:69]
	v_pk_mul_f32 v[64:65], v[60:61], v[64:65] op_sel_hi:[0,1]
	v_rcp_f32_e32 v58, v58
	v_rcp_f32_e32 v59, v59
	v_pk_mul_f32 v[56:57], v[56:57], v[64:65]
	v_pk_mul_f32 v[64:65], v[48:49], v[62:63] op_sel_hi:[1,0]
	v_pk_mul_f32 v[62:63], v[50:51], v[62:63] op_sel_hi:[1,0]
	v_exp_f32_e32 v64, v64
	v_exp_f32_e32 v65, v65
	v_pk_mul_f32 v[58:59], v[60:61], v[58:59] op_sel_hi:[0,1]
	v_exp_f32_e32 v62, v62
	v_exp_f32_e32 v63, v63
	v_pk_mul_f32 v[58:59], v[66:67], v[58:59]
	v_cvt_pk_bf16_f32 v56, v56, v57
	v_pk_mul_f32 v[48:49], v[48:49], v[52:53]
	v_cvt_pk_bf16_f32 v57, v58, v59
	v_pk_add_f32 v[58:59], v[64:65], 1.0 op_sel_hi:[1,0]
	v_pk_add_f32 v[52:53], v[62:63], 1.0 op_sel_hi:[1,0]
	v_rcp_f32_e32 v58, v58
; __host__ __device__ __forceinline__ size_t tl_off(int row, int k, int K) { return ((((size_t)(row >> 4) * (size_t)(K >> 5)) + (size_t)(k >> 5)) << 9) + (size_t)((row & 15) * 32 + (k & 31)); }
; __device__ __forceinline__ unsigned cvt_pk_bf16(float lo, float hi) { unsigned r; asm volatile("v_cvt_pk_bf16_f32 %0, %1, %2" : "=v"(r) : "v"(lo), "v"(hi)); return r; }
; #define PG8_BAR __builtin_amdgcn_s_barrier()
;     __device__ __forceinline__ void operator()(const f32x4 (&acc)[2][2][4][2], const Unit& u, int wr, int wc, int fr, int fq) const {
;     ...
;         for (int i = 0; i < 8; ++i) { const int ai = i >> 2, m = i & 3;
;             const float rstd = __builtin_amdgcn_rsqf(sv[i] * (1.0f / (float)D) + EPS), ne = -LOG2E * rstd, r2 = rstd * rstd;
;             unsigned w[4];
; #pragma unroll
;             for (int n = 0; n < 2; ++n)
; #pragma unroll
;                 for (int h = 0; h < 2; ++h) {
;                     const f32x2 g = {acc[ai][0][m][n][2 * h], acc[ai][0][m][n][2 * h + 1]}, up = {acc[ai][1][m][n][2 * h], acc[ai][1][m][n][2 * h + 1]};
;                     const f32x2 t = g * ne; f32x2 e; e.x = __builtin_amdgcn_exp2f(t.x); e.y = __builtin_amdgcn_exp2f(t.y);
;                     const f32x2 d = e + 1.0f; f32x2 r; r.x = __builtin_amdgcn_rcpf(d.x); r.y = __builtin_amdgcn_rcpf(d.y);
;                     const f32x2 a = (g * up) * (r * r2);
;                     w[2 * n + h] = cvt_pk_bf16(a.x, a.y); }
;             __builtin_nontemporal_store((u32x4){w[0], w[1], w[2], w[3]}, (u32x4*)(ACT + tl_off(row0 + ai * HALF + m * 16, col0, FF)));
;     ...
;         if (!has_next) break;
;         cur = nxt; cA = nA; cB = nB; ++ui;
;         if constexpr (ALIGN_EPI) { if (wr == 1) PG8_BAR; }
	v_rcp_f32_e32 v59, v59
	v_rcp_f32_e32 v52, v52
	v_rcp_f32_e32 v53, v53
	v_pk_mul_f32 v[50:51], v[50:51], v[54:55]
	v_pk_mul_f32 v[54:55], v[60:61], v[58:59] op_sel_hi:[0,1]
	v_pk_mul_f32 v[48:49], v[48:49], v[54:55]
	s_nop 0
	v_cvt_pk_bf16_f32 v58, v48, v49
	v_pk_mul_f32 v[48:49], v[60:61], v[52:53] op_sel_hi:[0,1]
	v_pk_mul_f32 v[48:49], v[50:51], v[48:49]
	s_nop 0
	v_cvt_pk_bf16_f32 v59, v48, v49
	v_fmamk_f32 v49, v141, 0x3a800000, v155
	v_rsq_f32_e32 v51, v49
	v_add_u32_e32 v48, 0x80, v156
	v_ashrrev_i32_e32 v48, 4, v48
	v_mad_i64_i32 v[48:49], s[0:1], v48, s75, v[136:137]
	v_mul_f32_e32 v50, 0xbfb8aa3b, v51
	v_pk_mul_f32 v[52:53], v[40:41], v[50:51] op_sel_hi:[1,0]
	v_pk_mul_f32 v[42:43], v[42:43], v[50:51] op_sel_hi:[1,0]
	v_exp_f32_e32 v52, v52
	v_exp_f32_e32 v53, v53
	v_exp_f32_e32 v42, v42
	v_exp_f32_e32 v43, v43
	v_lshlrev_b64 v[48:49], 10, v[48:49]
	v_pk_add_f32 v[52:53], v[52:53], 1.0 op_sel_hi:[1,0]
	v_lshl_add_u64 v[48:49], s[24:25], 0, v[48:49]
	v_rcp_f32_e32 v52, v52
	v_rcp_f32_e32 v53, v53
	v_lshl_add_u64 v[48:49], v[48:49], 0, v[128:129]
	global_store_dwordx4 v[48:49], v[56:59], off sc1
	v_mul_f32_e32 v48, v51, v51
	v_pk_add_f32 v[42:43], v[42:43], 1.0 op_sel_hi:[1,0]
	v_pk_mul_f32 v[40:41], v[40:41], v[44:45]
	v_pk_mul_f32 v[44:45], v[48:49], v[52:53] op_sel_hi:[0,1]
	v_rcp_f32_e32 v42, v42
	v_rcp_f32_e32 v43, v43
	v_pk_mul_f32 v[40:41], v[40:41], v[44:45]
	v_pk_mul_f32 v[44:45], v[32:33], v[50:51] op_sel_hi:[1,0]
	v_cvt_pk_bf16_f32 v40, v40, v41
	v_pk_mul_f32 v[42:43], v[48:49], v[42:43] op_sel_hi:[0,1]
	v_exp_f32_e32 v44, v44
	v_exp_f32_e32 v45, v45
	v_pk_mul_f32 v[42:43], v[46:47], v[42:43]
	v_pk_mul_f32 v[32:33], v[32:33], v[36:37]
	v_cvt_pk_bf16_f32 v41, v42, v43
	v_pk_add_f32 v[42:43], v[44:45], 1.0 op_sel_hi:[1,0]
	v_pk_mul_f32 v[44:45], v[34:35], v[50:51] op_sel_hi:[1,0]
	v_rcp_f32_e32 v42, v42
	v_exp_f32_e32 v44, v44
	v_exp_f32_e32 v45, v45
	v_rcp_f32_e32 v43, v43
	v_pk_mul_f32 v[34:35], v[34:35], v[38:39]
	v_pk_add_f32 v[36:37], v[44:45], 1.0 op_sel_hi:[1,0]
	s_nop 0
	v_rcp_f32_e32 v36, v36
	v_rcp_f32_e32 v37, v37
	v_pk_mul_f32 v[38:39], v[48:49], v[42:43] op_sel_hi:[0,1]
	v_pk_mul_f32 v[32:33], v[32:33], v[38:39]
	s_nop 0
	v_cvt_pk_bf16_f32 v42, v32, v33
	v_pk_mul_f32 v[32:33], v[48:49], v[36:37] op_sel_hi:[0,1]
	v_pk_mul_f32 v[32:33], v[34:35], v[32:33]
	s_nop 0
	v_cvt_pk_bf16_f32 v43, v32, v33
	s_waitcnt lgkmcnt(0)
	v_fmamk_f32 v33, v138, 0x3a800000, v155
	v_rsq_f32_e32 v35, v33
	v_add_u32_e32 v32, 0x90, v156
	v_ashrrev_i32_e32 v32, 4, v32
	v_mad_i64_i32 v[32:33], s[0:1], v32, s75, v[136:137]
	v_mul_f32_e32 v34, 0xbfb8aa3b, v35
	v_pk_mul_f32 v[36:37], v[24:25], v[34:35] op_sel_hi:[1,0]
	v_pk_mul_f32 v[26:27], v[26:27], v[34:35] op_sel_hi:[1,0]
	v_exp_f32_e32 v36, v36
	v_exp_f32_e32 v37, v37
	v_exp_f32_e32 v26, v26
	v_exp_f32_e32 v27, v27
	v_lshlrev_b64 v[32:33], 10, v[32:33]
	v_pk_add_f32 v[36:37], v[36:37], 1.0 op_sel_hi:[1,0]
	v_lshl_add_u64 v[32:33], s[24:25], 0, v[32:33]
	v_rcp_f32_e32 v36, v36
	v_rcp_f32_e32 v37, v37
	v_lshl_add_u64 v[32:33], v[32:33], 0, v[128:129]
	global_store_dwordx4 v[32:33], v[40:43], off sc1
	v_mul_f32_e32 v32, v35, v35
	v_pk_add_f32 v[26:27], v[26:27], 1.0 op_sel_hi:[1,0]
	v_pk_mul_f32 v[24:25], v[24:25], v[28:29]
	v_pk_mul_f32 v[28:29], v[32:33], v[36:37] op_sel_hi:[0,1]
	v_rcp_f32_e32 v26, v26
	v_rcp_f32_e32 v27, v27
	v_pk_mul_f32 v[24:25], v[24:25], v[28:29]
	v_pk_mul_f32 v[28:29], v[16:17], v[34:35] op_sel_hi:[1,0]
	v_cvt_pk_bf16_f32 v24, v24, v25
	v_pk_mul_f32 v[26:27], v[32:33], v[26:27] op_sel_hi:[0,1]
	v_exp_f32_e32 v28, v28
	v_exp_f32_e32 v29, v29
	v_pk_mul_f32 v[26:27], v[30:31], v[26:27]
	v_pk_mul_f32 v[16:17], v[16:17], v[20:21]
	v_cvt_pk_bf16_f32 v25, v26, v27
	v_pk_add_f32 v[26:27], v[28:29], 1.0 op_sel_hi:[1,0]
	v_pk_mul_f32 v[28:29], v[18:19], v[34:35] op_sel_hi:[1,0]
	v_rcp_f32_e32 v26, v26
	v_exp_f32_e32 v28, v28
	v_exp_f32_e32 v29, v29
	v_rcp_f32_e32 v27, v27
	v_pk_mul_f32 v[18:19], v[18:19], v[22:23]
	v_pk_add_f32 v[20:21], v[28:29], 1.0 op_sel_hi:[1,0]
	s_nop 0
	v_rcp_f32_e32 v20, v20
	v_rcp_f32_e32 v21, v21
	v_pk_mul_f32 v[22:23], v[32:33], v[26:27] op_sel_hi:[0,1]
	v_pk_mul_f32 v[16:17], v[16:17], v[22:23]
	s_nop 0
	v_cvt_pk_bf16_f32 v26, v16, v17
	v_pk_mul_f32 v[16:17], v[32:33], v[20:21] op_sel_hi:[0,1]
	v_pk_mul_f32 v[16:17], v[18:19], v[16:17]
	s_nop 0
	v_cvt_pk_bf16_f32 v27, v16, v17
	v_fmamk_f32 v17, v139, 0x3a800000, v155
	v_rsq_f32_e32 v19, v17
	v_add_u32_e32 v16, 0xa0, v156
	v_ashrrev_i32_e32 v16, 4, v16
	v_mad_i64_i32 v[16:17], s[0:1], v16, s75, v[136:137]
	v_mul_f32_e32 v18, 0xbfb8aa3b, v19
	v_pk_mul_f32 v[20:21], v[8:9], v[18:19] op_sel_hi:[1,0]
	v_pk_mul_f32 v[10:11], v[10:11], v[18:19] op_sel_hi:[1,0]
	v_exp_f32_e32 v20, v20
	v_exp_f32_e32 v21, v21
	v_exp_f32_e32 v10, v10
	v_exp_f32_e32 v11, v11
	v_lshlrev_b64 v[16:17], 10, v[16:17]
	v_pk_add_f32 v[20:21], v[20:21], 1.0 op_sel_hi:[1,0]
	v_lshl_add_u64 v[16:17], s[24:25], 0, v[16:17]
	v_rcp_f32_e32 v20, v20
	v_rcp_f32_e32 v21, v21
	v_lshl_add_u64 v[16:17], v[16:17], 0, v[128:129]
	global_store_dwordx4 v[16:17], v[24:27], off sc1
	v_mul_f32_e32 v16, v19, v19
	v_pk_add_f32 v[10:11], v[10:11], 1.0 op_sel_hi:[1,0]
	v_pk_mul_f32 v[8:9], v[8:9], v[12:13]
	v_pk_mul_f32 v[12:13], v[16:17], v[20:21] op_sel_hi:[0,1]
	v_rcp_f32_e32 v10, v10
	v_rcp_f32_e32 v11, v11
	v_pk_mul_f32 v[8:9], v[8:9], v[12:13]
	v_pk_mul_f32 v[12:13], v[0:1], v[18:19] op_sel_hi:[1,0]
	v_cvt_pk_bf16_f32 v8, v8, v9
	v_pk_mul_f32 v[10:11], v[16:17], v[10:11] op_sel_hi:[0,1]
	v_exp_f32_e32 v12, v12
	v_exp_f32_e32 v13, v13
	v_pk_mul_f32 v[10:11], v[14:15], v[10:11]
	v_pk_mul_f32 v[0:1], v[0:1], v[4:5]
	v_cvt_pk_bf16_f32 v9, v10, v11
	v_pk_add_f32 v[10:11], v[12:13], 1.0 op_sel_hi:[1,0]
	v_pk_mul_f32 v[12:13], v[2:3], v[18:19] op_sel_hi:[1,0]
	v_rcp_f32_e32 v10, v10
	v_exp_f32_e32 v12, v12
	v_exp_f32_e32 v13, v13
	v_rcp_f32_e32 v11, v11
	v_pk_mul_f32 v[2:3], v[2:3], v[6:7]
	v_pk_add_f32 v[4:5], v[12:13], 1.0 op_sel_hi:[1,0]
	s_nop 0
	v_rcp_f32_e32 v4, v4
	v_rcp_f32_e32 v5, v5
	v_pk_mul_f32 v[6:7], v[16:17], v[10:11] op_sel_hi:[0,1]
	v_pk_mul_f32 v[0:1], v[0:1], v[6:7]
	s_nop 0
	v_cvt_pk_bf16_f32 v10, v0, v1
	v_pk_mul_f32 v[0:1], v[16:17], v[4:5] op_sel_hi:[0,1]
	v_pk_mul_f32 v[0:1], v[2:3], v[0:1]
	s_nop 0
	v_cvt_pk_bf16_f32 v11, v0, v1
	v_add_u32_e32 v0, 0xb0, v156
	v_ashrrev_i32_e32 v0, 4, v0
	v_mad_i64_i32 v[0:1], s[0:1], v0, s75, v[136:137]
	v_lshlrev_b64 v[0:1], 10, v[0:1]
	v_lshl_add_u64 v[0:1], s[24:25], 0, v[0:1]
	v_lshl_add_u64 v[0:1], v[0:1], 0, v[128:129]
	global_store_dwordx4 v[0:1], v[8:11], off sc1
	s_cbranch_vccnz .LBB0_481
	s_andn2_b64 vcc, exec, s[6:7]
	s_cbranch_vccnz .LBB0_480
	s_barrier
	s_branch .LBB0_480
